# L1 gate/up conversion moved to idle WGs of layer-0 res1 phase; silu(c) staging batched; gla_out sigmoid division replaced by v_rcp_f32
# speedup vs baseline: 1.0327x; 1.0054x over previous
; __device__ __forceinline__ float sigmoidf_(float x) { return 1.f / (1.f + __expf(-x)); }
; __device__ __forceinline__ void mod_items(ArgsP a, LAS unsigned char* lds, int bid, int G, int wave, int lane) {
;     ...
;     for (int e = tid; e < 5 * DM; e += 512) { const int b5 = e >> 11, k = e & 2047; const float cvv = b5 < 4 ? a->in[1][b5 * DM + k] : a->in[3][k]; sil[e] = cvv * sigmoidf_(cvv); }
;     __syncthreads();
.LBB0_363:
	s_and_b32 s2, s33, 0xffffffc0
	v_or_b32_e32 v22, s2, v69
	s_movk_i32 s2, 0x2800
	v_cmp_gt_i32_e32 vcc, s2, v22
	s_barrier
	s_load_dwordx2 s[4:5], s[10:11], 0x8
	s_load_dwordx2 s[6:7], s[10:11], 0x18
	v_lshlrev_b32_e32 v2, 2, v22
	s_waitcnt lgkmcnt(0)
	global_load_dword v30, v2, s[4:5]
	s_add_u32 s12, s4, 0x800
	s_addc_u32 s13, s5, 0
	global_load_dword v31, v2, s[12:13]
	s_add_u32 s12, s4, 0x1000
	s_addc_u32 s13, s5, 0
	global_load_dword v32, v2, s[12:13]
	s_add_u32 s12, s4, 0x1800
	s_addc_u32 s13, s5, 0
	global_load_dword v33, v2, s[12:13]
	s_add_u32 s12, s4, 0x2000
	s_addc_u32 s13, s5, 0
	global_load_dword v34, v2, s[12:13]
	s_add_u32 s12, s4, 0x2800
	s_addc_u32 s13, s5, 0
	global_load_dword v35, v2, s[12:13]
	s_add_u32 s12, s4, 0x3000
	s_addc_u32 s13, s5, 0
	global_load_dword v36, v2, s[12:13]
	s_add_u32 s12, s4, 0x3800
	s_addc_u32 s13, s5, 0
	global_load_dword v37, v2, s[12:13]
	s_add_u32 s12, s4, 0x4000
	s_addc_u32 s13, s5, 0
	global_load_dword v38, v2, s[12:13]
	s_add_u32 s12, s4, 0x4800
	s_addc_u32 s13, s5, 0
	global_load_dword v39, v2, s[12:13]
	s_add_u32 s12, s4, 0x5000
	s_addc_u32 s13, s5, 0
	global_load_dword v40, v2, s[12:13]
	s_add_u32 s12, s4, 0x5800
	s_addc_u32 s13, s5, 0
	global_load_dword v41, v2, s[12:13]
	s_add_u32 s12, s4, 0x6000
	s_addc_u32 s13, s5, 0
	global_load_dword v42, v2, s[12:13]
	s_add_u32 s12, s4, 0x6800
	s_addc_u32 s13, s5, 0
	global_load_dword v43, v2, s[12:13]
	s_add_u32 s12, s4, 0x7000
	s_addc_u32 s13, s5, 0
	global_load_dword v44, v2, s[12:13]
	s_add_u32 s12, s4, 0x7800
	s_addc_u32 s13, s5, 0
	global_load_dword v45, v2, s[12:13]
	global_load_dword v46, v2, s[6:7]
	s_add_u32 s12, s6, 0x800
	s_addc_u32 s13, s7, 0
	global_load_dword v47, v2, s[12:13]
	s_add_u32 s12, s6, 0x1000
	s_addc_u32 s13, s7, 0
	global_load_dword v48, v2, s[12:13]
	s_add_u32 s12, s6, 0x1800
	s_addc_u32 s13, s7, 0
	global_load_dword v49, v2, s[12:13]
	s_waitcnt vmcnt(19)
	v_mul_f32_e32 v80, 0xbfb8aa3b, v30
	s_waitcnt vmcnt(18)
	v_mul_f32_e32 v81, 0xbfb8aa3b, v31
	s_waitcnt vmcnt(17)
	v_mul_f32_e32 v82, 0xbfb8aa3b, v32
	s_waitcnt vmcnt(16)
	v_mul_f32_e32 v83, 0xbfb8aa3b, v33
	s_waitcnt vmcnt(15)
	v_mul_f32_e32 v84, 0xbfb8aa3b, v34
	s_waitcnt vmcnt(14)
	v_mul_f32_e32 v85, 0xbfb8aa3b, v35
	s_waitcnt vmcnt(13)
	v_mul_f32_e32 v86, 0xbfb8aa3b, v36
	s_waitcnt vmcnt(12)
	v_mul_f32_e32 v87, 0xbfb8aa3b, v37
	s_waitcnt vmcnt(11)
	v_mul_f32_e32 v88, 0xbfb8aa3b, v38
	s_waitcnt vmcnt(10)
	v_mul_f32_e32 v89, 0xbfb8aa3b, v39
	s_waitcnt vmcnt(9)
	v_mul_f32_e32 v90, 0xbfb8aa3b, v40
	s_waitcnt vmcnt(8)
	v_mul_f32_e32 v91, 0xbfb8aa3b, v41
	s_waitcnt vmcnt(7)
	v_mul_f32_e32 v92, 0xbfb8aa3b, v42
	s_waitcnt vmcnt(6)
	v_mul_f32_e32 v93, 0xbfb8aa3b, v43
	s_waitcnt vmcnt(5)
	v_mul_f32_e32 v94, 0xbfb8aa3b, v44
	s_waitcnt vmcnt(4)
	v_mul_f32_e32 v95, 0xbfb8aa3b, v45
	s_waitcnt vmcnt(3)
	v_mul_f32_e32 v96, 0xbfb8aa3b, v46
	s_waitcnt vmcnt(2)
	v_mul_f32_e32 v97, 0xbfb8aa3b, v47
	s_waitcnt vmcnt(1)
	v_mul_f32_e32 v98, 0xbfb8aa3b, v48
	s_waitcnt vmcnt(0)
	v_mul_f32_e32 v99, 0xbfb8aa3b, v49
	v_exp_f32_e32 v80, v80
	v_exp_f32_e32 v81, v81
	v_exp_f32_e32 v82, v82
	v_exp_f32_e32 v83, v83
	v_exp_f32_e32 v84, v84
	v_exp_f32_e32 v85, v85
	v_exp_f32_e32 v86, v86
	v_exp_f32_e32 v87, v87
	v_exp_f32_e32 v88, v88
	v_exp_f32_e32 v89, v89
	v_exp_f32_e32 v90, v90
	v_exp_f32_e32 v91, v91
	v_exp_f32_e32 v92, v92
	v_exp_f32_e32 v93, v93
	v_exp_f32_e32 v94, v94
	v_exp_f32_e32 v95, v95
	v_exp_f32_e32 v96, v96
	v_exp_f32_e32 v97, v97
	v_exp_f32_e32 v98, v98
	v_exp_f32_e32 v99, v99
	v_add_f32_e32 v80, 1.0, v80
	v_add_f32_e32 v81, 1.0, v81
	v_add_f32_e32 v82, 1.0, v82
	v_add_f32_e32 v83, 1.0, v83
	v_add_f32_e32 v84, 1.0, v84
	v_add_f32_e32 v85, 1.0, v85
	v_add_f32_e32 v86, 1.0, v86
	v_add_f32_e32 v87, 1.0, v87
	v_add_f32_e32 v88, 1.0, v88
	v_add_f32_e32 v89, 1.0, v89
	v_add_f32_e32 v90, 1.0, v90
	v_add_f32_e32 v91, 1.0, v91
	v_add_f32_e32 v92, 1.0, v92
	v_add_f32_e32 v93, 1.0, v93
	v_add_f32_e32 v94, 1.0, v94
	v_add_f32_e32 v95, 1.0, v95
	v_add_f32_e32 v96, 1.0, v96
	v_add_f32_e32 v97, 1.0, v97
	v_add_f32_e32 v98, 1.0, v98
	v_add_f32_e32 v99, 1.0, v99
	v_rcp_f32_e32 v80, v80
	v_rcp_f32_e32 v81, v81
	v_rcp_f32_e32 v82, v82
	v_rcp_f32_e32 v83, v83
	v_rcp_f32_e32 v84, v84
	v_rcp_f32_e32 v85, v85
	v_rcp_f32_e32 v86, v86
	v_rcp_f32_e32 v87, v87
	v_rcp_f32_e32 v88, v88
	v_rcp_f32_e32 v89, v89
	v_rcp_f32_e32 v90, v90
	v_rcp_f32_e32 v91, v91
	v_rcp_f32_e32 v92, v92
	v_rcp_f32_e32 v93, v93
	v_rcp_f32_e32 v94, v94
	v_rcp_f32_e32 v95, v95
	v_rcp_f32_e32 v96, v96
	v_rcp_f32_e32 v97, v97
	v_rcp_f32_e32 v98, v98
	v_rcp_f32_e32 v99, v99
	v_mul_f32_e32 v30, v30, v80
	v_mul_f32_e32 v31, v31, v81
	v_mul_f32_e32 v32, v32, v82
	v_mul_f32_e32 v33, v33, v83
	v_mul_f32_e32 v34, v34, v84
	v_mul_f32_e32 v35, v35, v85
	v_mul_f32_e32 v36, v36, v86
	v_mul_f32_e32 v37, v37, v87
	v_mul_f32_e32 v38, v38, v88
	v_mul_f32_e32 v39, v39, v89
	v_mul_f32_e32 v40, v40, v90
	v_mul_f32_e32 v41, v41, v91
	v_mul_f32_e32 v42, v42, v92
	v_mul_f32_e32 v43, v43, v93
	v_mul_f32_e32 v44, v44, v94
	v_mul_f32_e32 v45, v45, v95
	v_mul_f32_e32 v46, v46, v96
	v_mul_f32_e32 v47, v47, v97
	v_mul_f32_e32 v48, v48, v98
	v_mul_f32_e32 v49, v49, v99
	ds_write_b32 v2, v30
	ds_write_b32 v2, v31 offset:2048
	ds_write_b32 v2, v32 offset:4096
	ds_write_b32 v2, v33 offset:6144
	ds_write_b32 v2, v34 offset:8192
	ds_write_b32 v2, v35 offset:10240
	ds_write_b32 v2, v36 offset:12288
	ds_write_b32 v2, v37 offset:14336
	ds_write_b32 v2, v38 offset:16384
	ds_write_b32 v2, v39 offset:18432
	ds_write_b32 v2, v40 offset:20480
	ds_write_b32 v2, v41 offset:22528
	ds_write_b32 v2, v42 offset:24576
	ds_write_b32 v2, v43 offset:26624
	ds_write_b32 v2, v44 offset:28672
	ds_write_b32 v2, v45 offset:30720
	ds_write_b32 v2, v46 offset:32768
	ds_write_b32 v2, v47 offset:34816
	ds_write_b32 v2, v48 offset:36864
	ds_write_b32 v2, v49 offset:38912
	s_cmpk_gt_i32 s30, 0x5f
	s_waitcnt lgkmcnt(0)
	s_barrier
	s_cbranch_scc1 .LBB0_378
	s_load_dwordx2 s[2:3], s[10:11], 0x20
	s_add_u32 s18, s16, 0x100000
	s_addc_u32 s19, s17, 0
	s_lshl_b32 s4, s31, 8
	s_mul_i32 s5, s31, 0xc00000
	s_mul_hi_i32 s4, s4, 0xc000
	s_waitcnt lgkmcnt(0)
	s_add_u32 s21, s2, s5
	s_addc_u32 s22, s3, s4
	s_lshl_b32 s2, s31, 10
	s_add_i32 s23, s2, 0
	v_lshl_add_u32 v2, v69, 4, 0
	s_movk_i32 s2, 0x500
	s_mulk_i32 s31, 0x1400
	v_lshlrev_b32_e32 v23, 2, v69
	s_mov_b32 s20, 0xc000
	v_cmp_gt_i32_e32 vcc, s2, v22
	s_mov_b32 s24, 0x18000
	s_mov_b32 s25, 0x24000
	s_mov_b32 s26, 0x30000
	s_mov_b32 s27, 0x3c000
	s_mov_b32 s28, 0x48000
	s_mov_b32 s29, 0x54000
	v_add_u32_e32 v28, s31, v2
	v_mov_b32_e32 v25, 0
	s_movk_i32 s31, 0x2ff
	v_mov_b32_e32 v29, 2
	s_mov_b32 s33, s30
	s_branch .LBB0_373

; #define IN(k) (PHON(k) && get_args()->ph_lo <= (k) && (k) < get_args()->ph_hi)
; #define SEAM(k) do { ArgsP q_ = get_args(); if (q_->ph_lo <= (k) && (k) + 1 < q_->ph_hi) { if ((k) == 0) cg::this_grid().sync(); else xcd_barrier((unsigned*)(q_->ws + WS_CTL) + CW_BAR, (volatile LAS unsigned*)(lds + 151 * 1024)); } } while (0)
; __device__ __forceinline__ void ph_norm(int l, int which, LAS unsigned char* lds) { PH_PRE
;     if (which == 0 && l > 0) convert_weights(a, l, lds, CV_GU_SPLIT, CV_GU_END, gw, NGW, wave, lane);
; __global__ void __launch_bounds__(512, 2) mega(Args a_unused) {
;     ...
;     for (int l = 0; l < 2; ++l) {
;         const int pb = 1 + 10 * l;
;         if (IN(pb)) ph_norm(l, 0, lds);
;         SEAM(pb);
.LBB0_403:
	s_mov_b64 s[2:3], s[0:1]
	s_load_dword s2, s[2:3], 0xd8
	s_xor_b64 s[6:7], s[66:67], -1
	v_writelane_b32 v255, s6, 6
	s_mul_i32 s87, s77, 10
	s_or_b32 s31, s87, 1
	v_writelane_b32 v255, s7, 7
	s_waitcnt lgkmcnt(0)
	s_cmp_gt_i32 s2, s31
	v_writelane_b32 v255, s77, 8
	s_cbranch_scc1 .LBB0_608
	s_mov_b64 s[2:3], s[0:1]
	s_load_dword s2, s[2:3], 0xdc
	s_waitcnt lgkmcnt(0)
	s_cmp_ge_i32 s31, s2
	s_cbranch_scc1 .LBB0_608
	s_mov_b64 s[14:15], s[0:1]
	s_waitcnt vmcnt(0)
	v_mov_b32_e32 v66, v206
	s_mov_b32 s3, s8
	v_readfirstlane_b32 s2, v66
	s_ashr_i32 s10, s2, 6
	s_load_dword s2, s[28:29], 0x0
	s_load_dwordx2 s[6:7], s[14:15], 0xd0
	s_lshl_b32 s3, s3, 3
	v_and_b32_e32 v64, 63, v66
	s_add_i32 s12, s3, s10
	s_waitcnt lgkmcnt(0)
	s_lshl_b32 s35, s2, 3
	s_andn2_b64 vcc, exec, s[4:5]
	s_mov_b32 s24, 0
	s_cbranch_vccnz .LBB0_583
	s_branch .LBB0_582
	s_cbranch_scc1 .LBB0_582
	s_add_i32 s13, s12, 0x27b0
	s_cmpk_gt_u32 s13, 0x30af
	s_mov_b64 s[16:17], -1
	s_cbranch_scc0 .LBB0_409
	s_add_i32 s2, s13, 0xcf50
	s_and_b32 s3, s2, 0xffff
	s_mul_i32 s3, s3, 0xba2f
	s_lshr_b32 s16, s3, 16
	s_lshr_b32 s3, s3, 23
	s_mulk_i32 s3, 0xb0
	s_sub_i32 s17, s2, s3
	s_load_dwordx2 s[2:3], s[14:15], 0xb0
	s_and_b32 s17, s17, 0xffff
	s_and_b32 s18, s16, 0xff80
	s_lshl_b32 s19, s17, 5
	s_mul_i32 s16, s18, 0x5800
	s_waitcnt lgkmcnt(0)
	s_add_u32 s2, s2, s16
	s_addc_u32 s3, s3, 0
	s_lshl_b32 s16, s17, 7
	s_add_u32 s2, s2, s16
	s_addc_u32 s3, s3, 0
	s_add_u32 s2, s2, 0x2c00000
	s_addc_u32 s3, s3, 0
	s_lshl_b32 s16, s17, 6
	s_and_b32 s16, s16, 0x3f00
	s_and_b32 s17, s19, 0x60
	s_or_b32 s16, s16, s17
	s_lshl_b32 s16, s16, 12
	s_add_u32 s16, s6, s16
	s_addc_u32 s17, s7, 0
	s_lshl_b32 s19, s18, 1
	s_add_u32 s16, s16, s19
	s_addc_u32 s17, s17, 0
	s_add_u32 s26, s16, 0x5480000
	s_addc_u32 s27, s17, 0
	s_mov_b64 s[16:17], 0

; __device__ __forceinline__ unsigned cvt_pk_bf16(float lo, float hi) { unsigned r; asm volatile("v_cvt_pk_bf16_f32 %0, %1, %2" : "=v"(r) : "v"(lo), "v"(hi)); return r; }
; __device__ __forceinline__ float bflo(unsigned w) { return __uint_as_float(w << 16); }
; __device__ __forceinline__ float bfhi(unsigned w) { return __uint_as_float(w & 0xffff0000u); }
; __device__ __forceinline__ float sigmoidf_(float x) { return 1.f / (1.f + __expf(-x)); }
; __device__ __forceinline__ void gla_out_rows(ArgsP a, int l, int gw, int NGW, int lane) {
;     ...
;     for (int row = gw; row < MR; row += NGW) {
;         u32x4 f[4], bb[4], rr[4];
; #pragma unroll
;         for (int i = 0; i < 4; ++i) { const int col = (lane + 64 * i) * 8; f[i] = *(const u32x4*)(OF + (size_t)row * 2048 + col); bb[i] = *(const u32x4*)(OB + (size_t)row * 2048 + col); rr[i] = *(const u32x4*)(Y + (size_t)row * NY + YR + col); }
; #pragma unroll
;         for (int i = 0; i < 4; ++i) { const int col = (lane + 64 * i) * 8;
;             float o[8]; float ss = 0.f;
; #pragma unroll
;             for (int q = 0; q < 4; ++q) { o[2 * q] = bflo(f[i][q]) + bflo(bb[i][q]); o[2 * q + 1] = bfhi(f[i][q]) + bfhi(bb[i][q]); ss += o[2 * q] * o[2 * q] + o[2 * q + 1] * o[2 * q + 1]; }
;             const float rstd = rsqrtf(wave_sum(ss) * (1.f / 512.f) + EPS);
;             float y[8];
; #pragma unroll
;             for (int q = 0; q < 4; ++q) { const float r0 = bflo(rr[i][q]), r1 = bfhi(rr[i][q]); y[2 * q] = o[2 * q] * rstd * (q < 2 ? g0[2 * q] : g1[2 * q - 4]) * r0 * sigmoidf_(r0); y[2 * q + 1] = o[2 * q + 1] * rstd * (q < 2 ? g0[2 * q + 1] : g1[2 * q - 3]) * r1 * sigmoidf_(r1); }
;             u32x4 w; w.x = cvt_pk_bf16(y[0], y[1]); w.y = cvt_pk_bf16(y[2], y[3]); w.z = cvt_pk_bf16(y[4], y[5]); w.w = cvt_pk_bf16(y[6], y[7]);
;             *(u32x4*)(OF + (size_t)row * 2048 + col) = w; }
.LBB0_1473:
	s_nop 0
	v_lshl_add_u64 v[8:9], s[12:13], 0, v[160:161]
	v_add_co_u32_e32 v36, vcc, 0x28700000, v8
	v_lshl_add_u64 v[10:11], s[6:7], 0, v[160:161]
	s_nop 0
	v_addc_co_u32_e32 v37, vcc, 0, v9, vcc
	v_add_co_u32_e32 v8, vcc, 0x2ab00000, v8
	global_load_dwordx4 v[44:47], v[36:37], off
	s_nop 0
	v_addc_co_u32_e32 v9, vcc, 0, v9, vcc
	global_load_dwordx4 v[48:51], v[8:9], off
	v_add_co_u32_e32 v10, vcc, 0x10202000, v10
	s_add_i32 s2, s2, s4
	s_nop 0
	v_addc_co_u32_e32 v11, vcc, 0, v11, vcc
	global_load_dwordx4 v[52:55], v[10:11], off
	global_load_dwordx4 v[56:59], v[36:37], off offset:1024
	global_load_dwordx4 v[60:63], v[8:9], off offset:1024
	global_load_dwordx4 v[32:35], v[10:11], off offset:1024
	global_load_dwordx4 v[24:27], v[36:37], off offset:2048
	global_load_dwordx4 v[28:31], v[8:9], off offset:2048
	global_load_dwordx4 v[20:23], v[10:11], off offset:2048
	global_load_dwordx4 v[12:15], v[36:37], off offset:3072
	global_load_dwordx4 v[16:19], v[8:9], off offset:3072
	s_nop 0
	global_load_dwordx4 v[8:11], v[10:11], off offset:3072
	s_add_u32 s6, s6, s10
	s_mul_hi_i32 s3, s4, 0x5800
	s_addc_u32 s7, s7, s3
	s_add_u32 s12, s12, s14
	s_addc_u32 s13, s13, s15
	s_cmpk_lt_i32 s2, 0x2400
	s_waitcnt vmcnt(11)
	v_lshlrev_b32_e32 v66, 16, v44
	v_lshlrev_b32_e32 v67, 16, v45
	v_and_b32_e32 v44, 0xffff0000, v44
	s_waitcnt vmcnt(10)
	v_lshlrev_b32_e32 v64, 16, v48
	v_lshlrev_b32_e32 v65, 16, v49
	v_and_b32_e32 v48, 0xffff0000, v48
	v_and_b32_e32 v49, 0xffff0000, v49
	v_and_b32_e32 v45, 0xffff0000, v45
	v_pk_add_f32 v[64:65], v[66:67], v[64:65]
	v_lshlrev_b32_e32 v67, 16, v50
	v_lshlrev_b32_e32 v69, 16, v46
	v_lshlrev_b32_e32 v66, 16, v51
	v_lshlrev_b32_e32 v68, 16, v47
	v_pk_add_f32 v[44:45], v[44:45], v[48:49]
	v_pk_mul_f32 v[48:49], v[64:65], v[64:65]
	v_and_b32_e32 v71, 0xffff0000, v50
	v_and_b32_e32 v73, 0xffff0000, v46
	v_and_b32_e32 v70, 0xffff0000, v51
	v_and_b32_e32 v72, 0xffff0000, v47
	v_pk_add_f32 v[46:47], v[68:69], v[66:67]
	v_pk_fma_f32 v[48:49], v[44:45], v[44:45], v[48:49]
	v_pk_add_f32 v[50:51], v[72:73], v[70:71]
	v_pk_mul_f32 v[66:67], v[46:47], v[46:47]
	v_add_f32_e32 v48, v48, v49
	v_pk_fma_f32 v[66:67], v[50:51], v[50:51], v[66:67]
	s_nop 0
	v_add_f32_e32 v48, v67, v48
	v_add_f32_e32 v48, v66, v48
	ds_bpermute_b32 v49, v38, v48
	s_waitcnt lgkmcnt(0)
	v_add_f32_e32 v48, v48, v49
	ds_bpermute_b32 v49, v39, v48
	s_waitcnt lgkmcnt(0)
	v_add_f32_e32 v48, v48, v49
	ds_bpermute_b32 v49, v40, v48
	s_waitcnt lgkmcnt(0)
	v_add_f32_e32 v48, v48, v49
	ds_bpermute_b32 v49, v41, v48
	s_waitcnt lgkmcnt(0)
	v_add_f32_e32 v48, v48, v49
	ds_bpermute_b32 v49, v42, v48
	s_waitcnt lgkmcnt(0)
	v_add_f32_e32 v48, v48, v49
	ds_bpermute_b32 v49, v43, v48
	s_waitcnt lgkmcnt(0)
	v_add_f32_e32 v48, v48, v49
	v_fmamk_f32 v48, v48, 0x3b000000, v207
	v_cmp_gt_f32_e32 vcc, s34, v48
	v_mul_f32_e32 v49, 0x4b800000, v48
	s_nop 0
	v_cndmask_b32_e32 v48, v48, v49, vcc
	v_rsq_f32_e32 v48, v48
	s_nop 0
	v_mul_f32_e32 v49, 0x45800000, v48
	v_cndmask_b32_e32 v48, v48, v49, vcc
	v_mul_f32_e32 v64, v64, v48
	s_waitcnt vmcnt(9)
	v_lshlrev_b32_e32 v49, 16, v52
	v_mul_f32_e32 v64, v4, v64
	v_mul_f32_e32 v64, v64, v49
	v_mul_f32_e32 v49, 0xbfb8aa3b, v49
	v_exp_f32_e32 v49, v49
	v_mul_f32_e32 v44, v44, v48
	v_and_b32_e32 v52, 0xffff0000, v52
	v_mul_f32_e32 v44, v5, v44
	v_add_f32_e32 v49, 1.0, v49
	v_mul_f32_e32 v44, v44, v52
	v_mul_f32_e32 v52, 0xbfb8aa3b, v52
	v_exp_f32_e32 v52, v52
	v_rcp_f32_e32 v49, v49
	s_nop 0
	v_add_f32_e32 v52, 1.0, v52
	v_mul_f32_e32 v49, v49, v64
	v_mul_f32_e32 v45, v45, v48
	v_mul_f32_e32 v45, v7, v45
	v_mul_f32_e32 v47, v47, v48
	v_rcp_f32_e32 v52, v52
	s_nop 0
	v_mul_f32_e32 v64, v65, v48
	v_mul_f32_e32 v44, v52, v44
	v_lshlrev_b32_e32 v52, 16, v53
	v_mul_f32_e32 v64, v6, v64
	v_mul_f32_e32 v64, v64, v52
	v_mul_f32_e32 v52, 0xbfb8aa3b, v52
	v_exp_f32_e32 v52, v52
	v_and_b32_e32 v53, 0xffff0000, v53
	v_mul_f32_e32 v45, v45, v53
	v_mul_f32_e32 v53, 0xbfb8aa3b, v53
	v_add_f32_e32 v52, 1.0, v52
	v_exp_f32_e32 v53, v53
	v_mul_f32_e32 v47, v0, v47
	v_mul_f32_e32 v51, v51, v48
	v_rcp_f32_e32 v52, v52
	s_nop 0
	v_add_f32_e32 v53, 1.0, v53
	v_mul_f32_e32 v52, v52, v64
	v_mul_f32_e32 v51, v1, v51
	v_mul_f32_e32 v46, v46, v48
	v_mul_f32_e32 v46, v2, v46
	v_rcp_f32_e32 v53, v53
	s_nop 0
	v_mul_f32_e32 v45, v53, v45
	v_lshlrev_b32_e32 v53, 16, v54
	v_mul_f32_e32 v47, v47, v53
	v_mul_f32_e32 v53, 0xbfb8aa3b, v53
	v_exp_f32_e32 v53, v53
	v_and_b32_e32 v54, 0xffff0000, v54
	v_mul_f32_e32 v51, v51, v54
	v_cvt_pk_bf16_f32 v44, v49, v44
	v_add_f32_e32 v53, 1.0, v53
	v_cvt_pk_bf16_f32 v45, v52, v45
	s_waitcnt vmcnt(7)
	v_and_b32_e32 v49, 0xffff0000, v61
	v_lshlrev_b32_e32 v52, 16, v59
	v_rcp_f32_e32 v53, v53
	s_nop 0
	v_mul_f32_e32 v47, v53, v47
	v_mul_f32_e32 v53, 0xbfb8aa3b, v54
	v_exp_f32_e32 v53, v53
	s_nop 0
	v_add_f32_e32 v53, 1.0, v53
	v_rcp_f32_e32 v53, v53
	s_nop 0
	v_mul_f32_e32 v51, v53, v51
	v_lshlrev_b32_e32 v53, 16, v55
	v_mul_f32_e32 v46, v46, v53
	v_mul_f32_e32 v53, 0xbfb8aa3b, v53
	v_exp_f32_e32 v53, v53
	v_and_b32_e32 v54, 0xffff0000, v55
	v_add_f32_e32 v53, 1.0, v53
	v_rcp_f32_e32 v53, v53
	s_nop 0
	v_mul_f32_e32 v53, v53, v46
	v_mul_f32_e32 v46, v50, v48
	v_mul_f32_e32 v48, 0xbfb8aa3b, v54
	v_exp_f32_e32 v48, v48
	v_mul_f32_e32 v46, v3, v46
	v_mul_f32_e32 v46, v46, v54
	v_add_f32_e32 v48, 1.0, v48
	v_rcp_f32_e32 v48, v48
	s_nop 0
	v_mul_f32_e32 v48, v48, v46
	v_cvt_pk_bf16_f32 v46, v47, v51
	v_cvt_pk_bf16_f32 v47, v53, v48
	global_store_dwordx4 v[36:37], v[44:47], off
	v_and_b32_e32 v48, 0xffff0000, v60
	v_and_b32_e32 v50, 0xffff0000, v56
	v_lshlrev_b32_e32 v44, 16, v60
	v_lshlrev_b32_e32 v46, 16, v56
	v_lshlrev_b32_e32 v45, 16, v61
	v_lshlrev_b32_e32 v47, 16, v57
	v_and_b32_e32 v51, 0xffff0000, v57
	v_pk_add_f32 v[44:45], v[46:47], v[44:45]
	v_pk_add_f32 v[46:47], v[50:51], v[48:49]
	v_lshlrev_b32_e32 v51, 16, v62
	v_lshlrev_b32_e32 v53, 16, v58
	v_lshlrev_b32_e32 v50, 16, v63
	v_pk_mul_f32 v[48:49], v[44:45], v[44:45]
	v_and_b32_e32 v55, 0xffff0000, v62
	v_and_b32_e32 v57, 0xffff0000, v58
	v_and_b32_e32 v54, 0xffff0000, v63
	v_and_b32_e32 v56, 0xffff0000, v59
	v_pk_add_f32 v[50:51], v[52:53], v[50:51]
	v_pk_fma_f32 v[48:49], v[46:47], v[46:47], v[48:49]
	v_pk_add_f32 v[52:53], v[56:57], v[54:55]
	v_pk_mul_f32 v[54:55], v[50:51], v[50:51]
	v_add_f32_e32 v48, v48, v49
	v_pk_fma_f32 v[54:55], v[52:53], v[52:53], v[54:55]
	s_nop 0
	v_add_f32_e32 v48, v55, v48
	v_add_f32_e32 v48, v54, v48
	ds_bpermute_b32 v49, v38, v48
	s_waitcnt lgkmcnt(0)
; __device__ __forceinline__ unsigned cvt_pk_bf16(float lo, float hi) { unsigned r; asm volatile("v_cvt_pk_bf16_f32 %0, %1, %2" : "=v"(r) : "v"(lo), "v"(hi)); return r; }
; __device__ __forceinline__ float bflo(unsigned w) { return __uint_as_float(w << 16); }
; __device__ __forceinline__ float bfhi(unsigned w) { return __uint_as_float(w & 0xffff0000u); }
; __device__ __forceinline__ float sigmoidf_(float x) { return 1.f / (1.f + __expf(-x)); }
; __device__ __forceinline__ void gla_out_rows(ArgsP a, int l, int gw, int NGW, int lane) {
;     ...
;         for (int i = 0; i < 4; ++i) { const int col = (lane + 64 * i) * 8;
;             float o[8]; float ss = 0.f;
; #pragma unroll
;             for (int q = 0; q < 4; ++q) { o[2 * q] = bflo(f[i][q]) + bflo(bb[i][q]); o[2 * q + 1] = bfhi(f[i][q]) + bfhi(bb[i][q]); ss += o[2 * q] * o[2 * q] + o[2 * q + 1] * o[2 * q + 1]; }
;             const float rstd = rsqrtf(wave_sum(ss) * (1.f / 512.f) + EPS);
;             float y[8];
; #pragma unroll
;             for (int q = 0; q < 4; ++q) { const float r0 = bflo(rr[i][q]), r1 = bfhi(rr[i][q]); y[2 * q] = o[2 * q] * rstd * (q < 2 ? g0[2 * q] : g1[2 * q - 4]) * r0 * sigmoidf_(r0); y[2 * q + 1] = o[2 * q + 1] * rstd * (q < 2 ? g0[2 * q + 1] : g1[2 * q - 3]) * r1 * sigmoidf_(r1); }
;             u32x4 w; w.x = cvt_pk_bf16(y[0], y[1]); w.y = cvt_pk_bf16(y[2], y[3]); w.z = cvt_pk_bf16(y[4], y[5]); w.w = cvt_pk_bf16(y[6], y[7]);
;             *(u32x4*)(OF + (size_t)row * 2048 + col) = w; }
	v_add_f32_e32 v48, v48, v49
	ds_bpermute_b32 v49, v39, v48
	s_waitcnt lgkmcnt(0)
	v_add_f32_e32 v48, v48, v49
	ds_bpermute_b32 v49, v40, v48
	s_waitcnt lgkmcnt(0)
	v_add_f32_e32 v48, v48, v49
	ds_bpermute_b32 v49, v41, v48
	s_waitcnt lgkmcnt(0)
	v_add_f32_e32 v48, v48, v49
	ds_bpermute_b32 v49, v42, v48
	s_waitcnt lgkmcnt(0)
	v_add_f32_e32 v48, v48, v49
	ds_bpermute_b32 v49, v43, v48
	s_waitcnt lgkmcnt(0)
	v_add_f32_e32 v48, v48, v49
	v_fmamk_f32 v48, v48, 0x3b000000, v207
	v_cmp_gt_f32_e32 vcc, s34, v48
	v_mul_f32_e32 v49, 0x4b800000, v48
	s_nop 0
	v_cndmask_b32_e32 v48, v48, v49, vcc
	v_rsq_f32_e32 v48, v48
	s_nop 0
	v_mul_f32_e32 v49, 0x45800000, v48
	v_cndmask_b32_e32 v48, v48, v49, vcc
	v_mul_f32_e32 v44, v44, v48
	s_waitcnt vmcnt(7)
	v_lshlrev_b32_e32 v49, 16, v32
	v_mul_f32_e32 v44, v4, v44
	v_mul_f32_e32 v44, v44, v49
	v_mul_f32_e32 v49, 0xbfb8aa3b, v49
	v_exp_f32_e32 v49, v49
	v_mul_f32_e32 v46, v46, v48
	v_and_b32_e32 v32, 0xffff0000, v32
	v_mul_f32_e32 v46, v5, v46
	v_add_f32_e32 v49, 1.0, v49
	v_mul_f32_e32 v46, v46, v32
	v_mul_f32_e32 v32, 0xbfb8aa3b, v32
	v_exp_f32_e32 v32, v32
	v_rcp_f32_e32 v49, v49
	s_nop 0
	v_add_f32_e32 v32, 1.0, v32
	v_mul_f32_e32 v44, v49, v44
	v_mul_f32_e32 v45, v45, v48
	v_mul_f32_e32 v45, v6, v45
	v_rcp_f32_e32 v32, v32
	s_nop 0
	v_mul_f32_e32 v32, v32, v46
	v_lshlrev_b32_e32 v46, 16, v33
	v_mul_f32_e32 v45, v45, v46
	v_mul_f32_e32 v46, 0xbfb8aa3b, v46
	v_exp_f32_e32 v46, v46
	v_and_b32_e32 v33, 0xffff0000, v33
	v_cvt_pk_bf16_f32 v32, v44, v32
	s_waitcnt vmcnt(6)
	v_lshlrev_b32_e32 v44, 16, v27
	v_add_f32_e32 v46, 1.0, v46
	v_rcp_f32_e32 v46, v46
	s_nop 0
	v_mul_f32_e32 v45, v46, v45
	v_mul_f32_e32 v46, v47, v48
	v_mul_f32_e32 v46, v7, v46
	v_mul_f32_e32 v46, v46, v33
	v_mul_f32_e32 v33, 0xbfb8aa3b, v33
	v_exp_f32_e32 v33, v33
	s_nop 0
	v_add_f32_e32 v33, 1.0, v33
	v_rcp_f32_e32 v33, v33
	s_nop 0
	v_mul_f32_e32 v47, v51, v48
	v_mul_f32_e32 v33, v33, v46
	v_lshlrev_b32_e32 v46, 16, v34
	v_mul_f32_e32 v47, v0, v47
	v_mul_f32_e32 v47, v47, v46
	v_mul_f32_e32 v46, 0xbfb8aa3b, v46
	v_exp_f32_e32 v46, v46
	v_and_b32_e32 v34, 0xffff0000, v34
	v_cvt_pk_bf16_f32 v33, v45, v33
	v_lshlrev_b32_e32 v45, 16, v26
	v_add_f32_e32 v46, 1.0, v46
	v_rcp_f32_e32 v46, v46
	s_nop 0
	v_mul_f32_e32 v46, v46, v47
	v_mul_f32_e32 v47, v53, v48
	v_mul_f32_e32 v47, v1, v47
	v_mul_f32_e32 v47, v47, v34
	v_mul_f32_e32 v34, 0xbfb8aa3b, v34
	v_exp_f32_e32 v34, v34
	s_nop 0
	v_add_f32_e32 v34, 1.0, v34
	v_rcp_f32_e32 v34, v34
	s_nop 0
	v_mul_f32_e32 v49, v50, v48
	v_mul_f32_e32 v34, v34, v47
	v_lshlrev_b32_e32 v47, 16, v35
	v_mul_f32_e32 v49, v2, v49
	v_mul_f32_e32 v49, v49, v47
	v_mul_f32_e32 v47, 0xbfb8aa3b, v47
	v_exp_f32_e32 v47, v47
	v_mul_f32_e32 v48, v52, v48
	v_and_b32_e32 v35, 0xffff0000, v35
	v_mul_f32_e32 v48, v3, v48
	v_add_f32_e32 v47, 1.0, v47
	v_mul_f32_e32 v48, v48, v35
	v_mul_f32_e32 v35, 0xbfb8aa3b, v35
	v_exp_f32_e32 v35, v35
	v_rcp_f32_e32 v47, v47
	s_nop 0
	v_add_f32_e32 v35, 1.0, v35
	v_mul_f32_e32 v47, v47, v49
	v_cvt_pk_bf16_f32 v34, v46, v34
	s_waitcnt vmcnt(5)
	v_and_b32_e32 v46, 0xffff0000, v31
	v_rcp_f32_e32 v35, v35
	s_nop 0
	v_mul_f32_e32 v35, v35, v48
	v_cvt_pk_bf16_f32 v35, v47, v35
	global_store_dwordx4 v[36:37], v[32:35], off offset:1024
	v_and_b32_e32 v47, 0xffff0000, v30
	v_and_b32_e32 v49, 0xffff0000, v26
	v_lshlrev_b32_e32 v32, 16, v28
	v_lshlrev_b32_e32 v34, 16, v24
	v_lshlrev_b32_e32 v33, 16, v29
	v_lshlrev_b32_e32 v35, 16, v25
	v_and_b32_e32 v28, 0xffff0000, v28
	v_and_b32_e32 v24, 0xffff0000, v24
	v_and_b32_e32 v29, 0xffff0000, v29
	v_and_b32_e32 v25, 0xffff0000, v25
	v_pk_add_f32 v[32:33], v[34:35], v[32:33]
	v_lshlrev_b32_e32 v35, 16, v30
	v_lshlrev_b32_e32 v34, 16, v31
	v_pk_add_f32 v[24:25], v[24:25], v[28:29]
	v_pk_mul_f32 v[28:29], v[32:33], v[32:33]
	v_and_b32_e32 v48, 0xffff0000, v27
	v_pk_add_f32 v[26:27], v[44:45], v[34:35]
	v_pk_fma_f32 v[28:29], v[24:25], v[24:25], v[28:29]
	v_pk_add_f32 v[30:31], v[48:49], v[46:47]
	v_pk_mul_f32 v[34:35], v[26:27], v[26:27]
	v_add_f32_e32 v28, v28, v29
	v_pk_fma_f32 v[34:35], v[30:31], v[30:31], v[34:35]
	s_nop 0
	v_add_f32_e32 v28, v35, v28
	v_add_f32_e32 v28, v34, v28
	ds_bpermute_b32 v29, v38, v28
	s_waitcnt lgkmcnt(0)
	v_add_f32_e32 v28, v28, v29
	ds_bpermute_b32 v29, v39, v28
	s_waitcnt lgkmcnt(0)
	v_add_f32_e32 v28, v28, v29
	ds_bpermute_b32 v29, v40, v28
	s_waitcnt lgkmcnt(0)
	v_add_f32_e32 v28, v28, v29
	ds_bpermute_b32 v29, v41, v28
	s_waitcnt lgkmcnt(0)
	v_add_f32_e32 v28, v28, v29
	ds_bpermute_b32 v29, v42, v28
	s_waitcnt lgkmcnt(0)
	v_add_f32_e32 v28, v28, v29
	ds_bpermute_b32 v29, v43, v28
	s_waitcnt lgkmcnt(0)
	v_add_f32_e32 v28, v28, v29
	v_fmamk_f32 v28, v28, 0x3b000000, v207
	v_cmp_gt_f32_e32 vcc, s34, v28
	v_mul_f32_e32 v29, 0x4b800000, v28
	s_nop 0
	v_cndmask_b32_e32 v28, v28, v29, vcc
	v_rsq_f32_e32 v28, v28
	s_nop 0
	v_mul_f32_e32 v29, 0x45800000, v28
	v_cndmask_b32_e32 v28, v28, v29, vcc
	v_mul_f32_e32 v32, v32, v28
	s_waitcnt vmcnt(5)
	v_lshlrev_b32_e32 v29, 16, v20
	v_mul_f32_e32 v32, v4, v32
	v_mul_f32_e32 v32, v32, v29
	v_mul_f32_e32 v29, 0xbfb8aa3b, v29
	v_exp_f32_e32 v29, v29
	v_mul_f32_e32 v24, v24, v28
	v_and_b32_e32 v20, 0xffff0000, v20
	v_mul_f32_e32 v24, v5, v24
	v_add_f32_e32 v29, 1.0, v29
	v_mul_f32_e32 v24, v24, v20
	v_mul_f32_e32 v20, 0xbfb8aa3b, v20
	v_exp_f32_e32 v20, v20
	v_rcp_f32_e32 v29, v29
	s_nop 0
	v_add_f32_e32 v20, 1.0, v20
	v_mul_f32_e32 v29, v29, v32
	v_mul_f32_e32 v25, v25, v28
	v_mul_f32_e32 v25, v7, v25
	v_mul_f32_e32 v27, v27, v28
	v_rcp_f32_e32 v20, v20
	s_nop 0
	v_mul_f32_e32 v32, v33, v28
	v_mul_f32_e32 v20, v20, v24
	v_lshlrev_b32_e32 v24, 16, v21
	v_mul_f32_e32 v32, v6, v32
	v_mul_f32_e32 v32, v32, v24
	v_mul_f32_e32 v24, 0xbfb8aa3b, v24
	v_exp_f32_e32 v24, v24
	v_and_b32_e32 v21, 0xffff0000, v21
	v_mul_f32_e32 v25, v25, v21
	v_mul_f32_e32 v21, 0xbfb8aa3b, v21
	v_add_f32_e32 v24, 1.0, v24
	v_exp_f32_e32 v21, v21
	v_mul_f32_e32 v27, v0, v27
	v_mul_f32_e32 v26, v26, v28
	v_rcp_f32_e32 v24, v24
	s_nop 0
	v_add_f32_e32 v21, 1.0, v21
	v_mul_f32_e32 v24, v24, v32
	v_mul_f32_e32 v26, v2, v26
	v_cvt_pk_bf16_f32 v20, v29, v20
	s_waitcnt vmcnt(4)
; __device__ __forceinline__ unsigned cvt_pk_bf16(float lo, float hi) { unsigned r; asm volatile("v_cvt_pk_bf16_f32 %0, %1, %2" : "=v"(r) : "v"(lo), "v"(hi)); return r; }
; __device__ __forceinline__ float bflo(unsigned w) { return __uint_as_float(w << 16); }
; __device__ __forceinline__ float bfhi(unsigned w) { return __uint_as_float(w & 0xffff0000u); }
; __device__ __forceinline__ float sigmoidf_(float x) { return 1.f / (1.f + __expf(-x)); }
; __device__ __forceinline__ void gla_out_rows(ArgsP a, int l, int gw, int NGW, int lane) {
;     ...
;         for (int i = 0; i < 4; ++i) { const int col = (lane + 64 * i) * 8;
;             float o[8]; float ss = 0.f;
; #pragma unroll
;             for (int q = 0; q < 4; ++q) { o[2 * q] = bflo(f[i][q]) + bflo(bb[i][q]); o[2 * q + 1] = bfhi(f[i][q]) + bfhi(bb[i][q]); ss += o[2 * q] * o[2 * q] + o[2 * q + 1] * o[2 * q + 1]; }
;             const float rstd = rsqrtf(wave_sum(ss) * (1.f / 512.f) + EPS);
;             float y[8];
; #pragma unroll
;             for (int q = 0; q < 4; ++q) { const float r0 = bflo(rr[i][q]), r1 = bfhi(rr[i][q]); y[2 * q] = o[2 * q] * rstd * (q < 2 ? g0[2 * q] : g1[2 * q - 4]) * r0 * sigmoidf_(r0); y[2 * q + 1] = o[2 * q + 1] * rstd * (q < 2 ? g0[2 * q + 1] : g1[2 * q - 3]) * r1 * sigmoidf_(r1); }
;             u32x4 w; w.x = cvt_pk_bf16(y[0], y[1]); w.y = cvt_pk_bf16(y[2], y[3]); w.z = cvt_pk_bf16(y[4], y[5]); w.w = cvt_pk_bf16(y[6], y[7]);
;             *(u32x4*)(OF + (size_t)row * 2048 + col) = w; }
	v_and_b32_e32 v29, 0xffff0000, v14
	v_rcp_f32_e32 v21, v21
	s_nop 0
	v_mul_f32_e32 v21, v21, v25
	v_lshlrev_b32_e32 v25, 16, v22
	v_mul_f32_e32 v27, v27, v25
	v_mul_f32_e32 v25, 0xbfb8aa3b, v25
	v_exp_f32_e32 v25, v25
	v_and_b32_e32 v22, 0xffff0000, v22
	v_cvt_pk_bf16_f32 v21, v24, v21
	v_lshlrev_b32_e32 v24, 16, v15
	v_add_f32_e32 v25, 1.0, v25
	v_rcp_f32_e32 v25, v25
	s_nop 0
	v_mul_f32_e32 v25, v25, v27
	v_mul_f32_e32 v27, v31, v28
	v_mul_f32_e32 v27, v1, v27
	v_mul_f32_e32 v27, v27, v22
	v_mul_f32_e32 v22, 0xbfb8aa3b, v22
	v_exp_f32_e32 v22, v22
	s_nop 0
	v_add_f32_e32 v22, 1.0, v22
	v_rcp_f32_e32 v22, v22
	s_nop 0
	v_mul_f32_e32 v22, v22, v27
	v_lshlrev_b32_e32 v27, 16, v23
	v_mul_f32_e32 v26, v26, v27
	v_mul_f32_e32 v27, 0xbfb8aa3b, v27
	v_exp_f32_e32 v27, v27
	v_and_b32_e32 v23, 0xffff0000, v23
	v_cvt_pk_bf16_f32 v22, v25, v22
	v_lshlrev_b32_e32 v25, 16, v14
	v_add_f32_e32 v27, 1.0, v27
	v_rcp_f32_e32 v27, v27
	s_nop 0
	v_mul_f32_e32 v26, v27, v26
	v_mul_f32_e32 v27, v30, v28
	v_mul_f32_e32 v27, v3, v27
	v_mul_f32_e32 v27, v27, v23
	v_mul_f32_e32 v23, 0xbfb8aa3b, v23
	v_exp_f32_e32 v23, v23
	s_nop 0
	v_add_f32_e32 v23, 1.0, v23
	v_rcp_f32_e32 v23, v23
	s_nop 0
	v_mul_f32_e32 v23, v23, v27
	v_cvt_pk_bf16_f32 v23, v26, v23
	global_store_dwordx4 v[36:37], v[20:23], off offset:2048
	s_waitcnt vmcnt(4)
	v_and_b32_e32 v27, 0xffff0000, v18
	v_and_b32_e32 v26, 0xffff0000, v19
	v_lshlrev_b32_e32 v20, 16, v16
	v_lshlrev_b32_e32 v22, 16, v12
	v_lshlrev_b32_e32 v21, 16, v17
	v_lshlrev_b32_e32 v23, 16, v13
	v_and_b32_e32 v16, 0xffff0000, v16
	v_and_b32_e32 v12, 0xffff0000, v12
	v_and_b32_e32 v17, 0xffff0000, v17
	v_and_b32_e32 v13, 0xffff0000, v13
	v_pk_add_f32 v[20:21], v[22:23], v[20:21]
	v_lshlrev_b32_e32 v23, 16, v18
	v_lshlrev_b32_e32 v22, 16, v19
	v_pk_add_f32 v[12:13], v[12:13], v[16:17]
	v_pk_mul_f32 v[16:17], v[20:21], v[20:21]
	v_and_b32_e32 v28, 0xffff0000, v15
	v_pk_add_f32 v[14:15], v[24:25], v[22:23]
	v_pk_fma_f32 v[16:17], v[12:13], v[12:13], v[16:17]
	v_pk_add_f32 v[18:19], v[28:29], v[26:27]
	v_pk_mul_f32 v[22:23], v[14:15], v[14:15]
	v_add_f32_e32 v16, v16, v17
	v_pk_fma_f32 v[22:23], v[18:19], v[18:19], v[22:23]
	s_nop 0
	v_add_f32_e32 v16, v23, v16
	v_add_f32_e32 v16, v22, v16
	ds_bpermute_b32 v17, v38, v16
	s_waitcnt lgkmcnt(0)
	v_add_f32_e32 v16, v16, v17
	ds_bpermute_b32 v17, v39, v16
	s_waitcnt lgkmcnt(0)
	v_add_f32_e32 v16, v16, v17
	ds_bpermute_b32 v17, v40, v16
	s_waitcnt lgkmcnt(0)
	v_add_f32_e32 v16, v16, v17
	ds_bpermute_b32 v17, v41, v16
	s_waitcnt lgkmcnt(0)
	v_add_f32_e32 v16, v16, v17
	ds_bpermute_b32 v17, v42, v16
	s_waitcnt lgkmcnt(0)
	v_add_f32_e32 v16, v16, v17
	ds_bpermute_b32 v17, v43, v16
	s_waitcnt lgkmcnt(0)
	v_add_f32_e32 v16, v16, v17
	v_fmamk_f32 v16, v16, 0x3b000000, v207
	v_cmp_gt_f32_e32 vcc, s34, v16
	v_mul_f32_e32 v17, 0x4b800000, v16
	s_nop 0
	v_cndmask_b32_e32 v16, v16, v17, vcc
	v_rsq_f32_e32 v16, v16
	s_nop 0
	v_mul_f32_e32 v17, 0x45800000, v16
	v_cndmask_b32_e32 v16, v16, v17, vcc
	v_mul_f32_e32 v20, v20, v16
	s_waitcnt vmcnt(3)
	v_lshlrev_b32_e32 v17, 16, v8
	v_mul_f32_e32 v20, v4, v20
	v_mul_f32_e32 v20, v20, v17
	v_mul_f32_e32 v17, 0xbfb8aa3b, v17
	v_exp_f32_e32 v17, v17
	v_mul_f32_e32 v12, v12, v16
	v_and_b32_e32 v8, 0xffff0000, v8
	v_mul_f32_e32 v12, v5, v12
	v_add_f32_e32 v17, 1.0, v17
	v_mul_f32_e32 v12, v12, v8
	v_mul_f32_e32 v8, 0xbfb8aa3b, v8
	v_exp_f32_e32 v8, v8
	v_rcp_f32_e32 v17, v17
	s_nop 0
	v_add_f32_e32 v8, 1.0, v8
	v_mul_f32_e32 v17, v17, v20
	v_mul_f32_e32 v13, v13, v16
	v_mul_f32_e32 v13, v7, v13
	v_mul_f32_e32 v15, v15, v16
	v_rcp_f32_e32 v8, v8
	s_nop 0
	v_mul_f32_e32 v20, v21, v16
	v_mul_f32_e32 v8, v8, v12
	v_lshlrev_b32_e32 v12, 16, v9
	v_mul_f32_e32 v20, v6, v20
	v_mul_f32_e32 v20, v20, v12
	v_mul_f32_e32 v12, 0xbfb8aa3b, v12
	v_exp_f32_e32 v12, v12
	v_and_b32_e32 v9, 0xffff0000, v9
	v_mul_f32_e32 v13, v13, v9
	v_mul_f32_e32 v9, 0xbfb8aa3b, v9
	v_add_f32_e32 v12, 1.0, v12
	v_exp_f32_e32 v9, v9
	v_mul_f32_e32 v15, v0, v15
	v_mul_f32_e32 v14, v14, v16
	v_rcp_f32_e32 v12, v12
	s_nop 0
	v_add_f32_e32 v9, 1.0, v9
	v_mul_f32_e32 v12, v12, v20
	v_mul_f32_e32 v14, v2, v14
	v_cvt_pk_bf16_f32 v8, v17, v8
	v_rcp_f32_e32 v9, v9
	s_nop 0
	v_mul_f32_e32 v9, v9, v13
	v_lshlrev_b32_e32 v13, 16, v10
	v_mul_f32_e32 v15, v15, v13
	v_mul_f32_e32 v13, 0xbfb8aa3b, v13
	v_exp_f32_e32 v13, v13
	v_and_b32_e32 v10, 0xffff0000, v10
	v_cvt_pk_bf16_f32 v9, v12, v9
	v_add_f32_e32 v13, 1.0, v13
	v_rcp_f32_e32 v13, v13
	s_nop 0
	v_mul_f32_e32 v13, v13, v15
	v_mul_f32_e32 v15, v19, v16
	v_mul_f32_e32 v15, v1, v15
	v_mul_f32_e32 v15, v15, v10
	v_mul_f32_e32 v10, 0xbfb8aa3b, v10
	v_exp_f32_e32 v10, v10
	s_nop 0
	v_add_f32_e32 v10, 1.0, v10
	v_rcp_f32_e32 v10, v10
	s_nop 0
	v_mul_f32_e32 v10, v10, v15
	v_lshlrev_b32_e32 v15, 16, v11
	v_mul_f32_e32 v14, v14, v15
	v_mul_f32_e32 v15, 0xbfb8aa3b, v15
	v_exp_f32_e32 v15, v15
	v_and_b32_e32 v11, 0xffff0000, v11
	v_cvt_pk_bf16_f32 v10, v13, v10
	v_add_f32_e32 v15, 1.0, v15
	v_rcp_f32_e32 v15, v15
	s_nop 0
	v_mul_f32_e32 v14, v15, v14
	v_mul_f32_e32 v15, v18, v16
	v_mul_f32_e32 v15, v3, v15
	v_mul_f32_e32 v15, v15, v11
	v_mul_f32_e32 v11, 0xbfb8aa3b, v11
	v_exp_f32_e32 v11, v11
	s_nop 0
	v_add_f32_e32 v11, 1.0, v11
	v_rcp_f32_e32 v11, v11
	s_nop 0
	v_mul_f32_e32 v11, v11, v15
	v_cvt_pk_bf16_f32 v11, v14, v11
	global_store_dwordx4 v[36:37], v[8:11], off offset:3072
	s_cbranch_scc1 .LBB0_1473

; #define LAS __attribute__((address_space(3)))
; #define TRSET(W_, N_, WT_, LDD_, KOFF_, DROW_, KB_, N0_) do { p.k0 = 128 * (KB_); p.N = (N_); p.src = (W_) + (size_t)p.k0 * (N_) + (N0_); p.ldd = (LDD_); p.dst = (WT_) + (size_t)(DROW_) * (LDD_) + (KOFF_) + p.k0; } while (0)
; #define TR_LOAD(P_) do { const float* s_ = (P_).src + (size_t)(lane >> 3) * (P_).N + 4 * (lane & 7); _Pragma("unroll") for (int i = 0; i < 16; ++i) v[i] = __builtin_nontemporal_load((const f32x4*)(s_ + (size_t)(8 * i) * (P_).N)); } while (0)
; __device__ __forceinline__ TrP tr_decode(ArgsP a, int l, int it) {
;     ...
;     if (r < I_G) { const int kb = r / 176, nb = r % 176, n0 = 32 * nb; TRSET(a->in[21] + (size_t)l * DM * DFF, DFF, (bf16_t*)(ws + WS_WGU), DM, 0, (n0 >> 7) * 256 + (n0 & 127), kb, n0); return p; } r -= I_G;
;     if (r < I_G) { const int kb = r / 176, nb = r % 176, n0 = 32 * nb; TRSET(a->in[22] + (size_t)l * DM * DFF, DFF, (bf16_t*)(ws + WS_WGU), DM, 0, (n0 >> 7) * 256 + 128 + (n0 & 127), kb, n0); return p; } r -= I_G;
;     { const int kb = r / 64, nb = r % 64; TRSET(a->in[23] + (size_t)l * DFF * DM, DM, (bf16_t*)(ws + WS_WD), DFF, 0, 32 * nb, kb, 32 * nb); }
; __device__ __forceinline__ void convert_weights(ArgsP a, int l, LAS unsigned char* lds, int lo, int hi, int widx, int nw, int wave, int lane) {
;     ...
;     int it = lo + widx; if (widx < 0 || it >= hi) return;
;     TrP p = tr_decode(a, l, it);
;     ...
;     TR_LOAD(p);
;     for (;;) {
; #pragma unroll
;         for (int i = 0; i < 16; ++i) { LAS float* d = scr + (8 * i + (lane >> 3)) * 33 + 4 * (lane & 7); d[0] = v[i][0]; d[1] = v[i][1]; d[2] = v[i][2]; d[3] = v[i][3]; }
;         const int itn = it + nw; const bool more = itn < hi; TrP pn = p;
;         if (more) { pn = tr_decode(a, l, itn); TR_LOAD(pn); }
.LBB0_3385:
	s_and_b64 vcc, exec, s[66:67]
	s_cbranch_vccz .Lmy_cvr_done
	s_cmp_lt_u32 s8, 128
	s_cbranch_scc1 .Lmy_cvr_done
	v_and_b32_e32 v0, 63, v206
	v_lshrrev_b32_e32 v1, 6, v206
	s_load_dwordx2 s[14:15], s[0:1], 0xa8
	s_load_dwordx2 s[16:17], s[0:1], 0xb0
	s_load_dwordx2 s[18:19], s[0:1], 0xb8
	s_load_dwordx2 s[20:21], s[0:1], 0xd0
	v_readfirstlane_b32 s2, v1
	v_lshrrev_b32_e32 v2, 3, v0
	v_and_b32_e32 v3, 7, v0
	v_lshrrev_b32_e32 v5, 4, v0
	v_and_b32_e32 v6, 15, v0
	s_nop 3
	s_sub_i32 s3, s8, 128
	s_lshl_b32 s3, s3, 3
	s_add_i32 s3, s3, s2
	s_add_i32 s3, s3, 512
	s_mul_i32 s4, s2, 0x4400
	v_mul_u32_u24_e32 v4, 0x84, v2
	v_lshl_add_u32 v4, v3, 4, v4
	v_add_u32_e32 v4, s4, v4
	v_mul_u32_u24_e32 v7, 0x420, v5
	v_lshl_add_u32 v7, v6, 2, v7
	v_add_u32_e32 v7, s4, v7
	v_mul_u32_u24_e32 v8, 0x5800, v2
	v_lshl_add_u32 v8, v3, 4, v8
	v_lshlrev_b32_e32 v9, 13, v2
	v_lshl_add_u32 v9, v3, 4, v9
	v_lshlrev_b32_e32 v10, 12, v6
	v_lshl_add_u32 v10, v5, 4, v10
	v_add_u32_e32 v12, 0x10000, v10
	v_mul_u32_u24_e32 v11, 0x2c00, v6
	v_lshl_add_u32 v11, v5, 4, v11
	v_add_u32_e32 v13, 0x2c000, v11
	s_waitcnt lgkmcnt(0)
	s_add_u32 s22, s20, 0x5400000
	s_addc_u32 s23, s21, 0
	s_add_u32 s24, s20, 0x8000000
	s_addc_u32 s25, s21, 0
	s_cmp_ge_u32 s3, 5632
	s_cbranch_scc1 .Lmy_cvr_exit
	s_cmp_ge_u32 s3, 0x1600
	s_cbranch_scc1 .Lmy_cvr_dn0
	s_cmp_ge_u32 s3, 0xb00
	s_cselect_b32 s5, 0xb00, 0
	s_cselect_b32 s6, 128, 0
	s_cselect_b32 s26, s16, s14
	s_cselect_b32 s27, s17, s15
	s_sub_i32 s5, s3, s5
	s_mul_i32 s7, s5, 0xba2f
	s_lshr_b32 s7, s7, 23
	s_mul_i32 s10, s7, 0xb0
	s_sub_i32 s10, s5, s10
	s_mul_hi_u32 s35, s7, 0x2c0000
	s_mul_i32 s70, s7, 0x2c0000
	s_add_u32 s26, s26, s70
	s_addc_u32 s27, s27, s35
	s_add_u32 s26, s26, 0x2c00000
	s_addc_u32 s27, s27, 0
	s_lshl_b32 s70, s10, 7
	s_add_u32 s26, s26, s70
	s_addc_u32 s27, s27, 0
	s_lshr_b32 s70, s10, 2
	s_lshl_b32 s70, s70, 8
	s_and_b32 s71, s10, 3
	s_lshl_b32 s71, s71, 5
	s_add_i32 s70, s70, s71
	s_add_i32 s70, s70, s6
	s_lshl_b32 s70, s70, 12
	s_lshl_b32 s71, s7, 8
	s_add_i32 s70, s70, s71
	s_add_u32 s68, s22, s70
	s_addc_u32 s69, s23, 0
	s_mov_b32 s31, 0x2c000
	s_mov_b32 s72, 0
	v_mov_b32_e32 v1, v8
	s_branch .Lmy_cvr_ld0
.Lmy_cvr_dn0:
	s_sub_i32 s5, s3, 0x1600
	s_lshr_b32 s7, s5, 6
	s_and_b32 s10, s5, 63
	s_lshl_b32 s70, s7, 20
	s_lshr_b32 s35, s7, 12
	s_add_u32 s26, s18, s70
	s_addc_u32 s27, s19, s35
	s_lshl_b32 s70, s10, 7
	s_add_u32 s26, s26, s70
	s_addc_u32 s27, s27, 0
	s_mul_i32 s70, s10, 0x58000
	s_lshl_b32 s71, s7, 8
	s_add_i32 s70, s70, s71
	s_add_u32 s68, s24, s70
	s_addc_u32 s69, s25, 0
	s_mov_b32 s31, 0x10000
	s_mov_b32 s72, 1
	v_mov_b32_e32 v1, v9

; #define TRSET(W_, N_, WT_, LDD_, KOFF_, DROW_, KB_, N0_) do { p.k0 = 128 * (KB_); p.N = (N_); p.src = (W_) + (size_t)p.k0 * (N_) + (N0_); p.ldd = (LDD_); p.dst = (WT_) + (size_t)(DROW_) * (LDD_) + (KOFF_) + p.k0; } while (0)
; #define TR_LOAD(P_) do { const float* s_ = (P_).src + (size_t)(lane >> 3) * (P_).N + 4 * (lane & 7); _Pragma("unroll") for (int i = 0; i < 16; ++i) v[i] = __builtin_nontemporal_load((const f32x4*)(s_ + (size_t)(8 * i) * (P_).N)); } while (0)
; __device__ __forceinline__ TrP tr_decode(ArgsP a, int l, int it) {
;     ...
;     if (r < I_G) { const int kb = r / 176, nb = r % 176, n0 = 32 * nb; TRSET(a->in[21] + (size_t)l * DM * DFF, DFF, (bf16_t*)(ws + WS_WGU), DM, 0, (n0 >> 7) * 256 + (n0 & 127), kb, n0); return p; } r -= I_G;
;     if (r < I_G) { const int kb = r / 176, nb = r % 176, n0 = 32 * nb; TRSET(a->in[22] + (size_t)l * DM * DFF, DFF, (bf16_t*)(ws + WS_WGU), DM, 0, (n0 >> 7) * 256 + 128 + (n0 & 127), kb, n0); return p; } r -= I_G;
;     { const int kb = r / 64, nb = r % 64; TRSET(a->in[23] + (size_t)l * DFF * DM, DM, (bf16_t*)(ws + WS_WD), DFF, 0, 32 * nb, kb, 32 * nb); }
; __device__ __forceinline__ void convert_weights(ArgsP a, int l, LAS unsigned char* lds, int lo, int hi, int widx, int nw, int wave, int lane) {
;     ...
;         const int itn = it + nw; const bool more = itn < hi; TrP pn = p;
;         if (more) { pn = tr_decode(a, l, itn); TR_LOAD(pn); }
.Lmy_cvr_mid:
	s_waitcnt lgkmcnt(0)
	s_mov_b64 s[12:13], s[68:69]
	s_cmp_eq_u32 s72, 0
	s_cselect_b64 vcc, -1, 0
	v_cndmask_b32_e32 v3, v11, v10, vcc
	v_cndmask_b32_e32 v5, v13, v12, vcc
	s_add_i32 s3, s3, 1024
	s_cmp_ge_u32 s3, 5632
	s_cbranch_scc1 .Lmy_cvr_rd
	s_cmp_ge_u32 s3, 0x1600
	s_cbranch_scc1 .Lmy_cvr_dn1
	s_cmp_ge_u32 s3, 0xb00
	s_cselect_b32 s5, 0xb00, 0
	s_cselect_b32 s6, 128, 0
	s_cselect_b32 s26, s16, s14
	s_cselect_b32 s27, s17, s15
	s_sub_i32 s5, s3, s5
	s_mul_i32 s7, s5, 0xba2f
	s_lshr_b32 s7, s7, 23
	s_mul_i32 s10, s7, 0xb0
	s_sub_i32 s10, s5, s10
	s_mul_hi_u32 s35, s7, 0x2c0000
	s_mul_i32 s70, s7, 0x2c0000
	s_add_u32 s26, s26, s70
	s_addc_u32 s27, s27, s35
	s_add_u32 s26, s26, 0x2c00000
	s_addc_u32 s27, s27, 0
	s_lshl_b32 s70, s10, 7
	s_add_u32 s26, s26, s70
	s_addc_u32 s27, s27, 0
	s_lshr_b32 s70, s10, 2
	s_lshl_b32 s70, s70, 8
	s_and_b32 s71, s10, 3
	s_lshl_b32 s71, s71, 5
	s_add_i32 s70, s70, s71
	s_add_i32 s70, s70, s6
	s_lshl_b32 s70, s70, 12
	s_lshl_b32 s71, s7, 8
	s_add_i32 s70, s70, s71
	s_add_u32 s68, s22, s70
	s_addc_u32 s69, s23, 0
	s_mov_b32 s31, 0x2c000
	s_mov_b32 s72, 0
	v_mov_b32_e32 v1, v8
	s_branch .Lmy_cvr_ld1

; #define LAS __attribute__((address_space(3)))
; __device__ __forceinline__ unsigned cvt_pk_bf16(float lo, float hi) { unsigned r; asm volatile("v_cvt_pk_bf16_f32 %0, %1, %2" : "=v"(r) : "v"(lo), "v"(hi)); return r; }
; __device__ __forceinline__ void convert_weights(ArgsP a, int l, LAS unsigned char* lds, int lo, int hi, int widx, int nw, int wave, int lane) {
;     ...
;         asm volatile("s_waitcnt lgkmcnt(0)" ::: "memory");
; #pragma unroll
;         for (int j = 0; j < 8; ++j) { const int n = (lane & 15) + 16 * (j & 1), ch = (lane >> 4) + 4 * (j >> 1); const LAS float* sp = scr + (8 * ch) * 33 + n;
;             float gs[8];
; #pragma unroll
;             for (int e = 0; e < 8; ++e) gs[e] = p.gk ? p.gk[p.k0 + 8 * ch + e] : 1.f;
;             u32x4 o; o.x = cvt_pk_bf16(sp[0 * 33] * gs[0], sp[1 * 33] * gs[1]); o.y = cvt_pk_bf16(sp[2 * 33] * gs[2], sp[3 * 33] * gs[3]); o.z = cvt_pk_bf16(sp[4 * 33] * gs[4], sp[5 * 33] * gs[5]); o.w = cvt_pk_bf16(sp[6 * 33] * gs[6], sp[7 * 33] * gs[7]);
;             *(u32x4*)(p.dst + (size_t)n * p.ldd + 8 * ch) = o; }
;         asm volatile("s_waitcnt lgkmcnt(0)" ::: "memory");
;         if (!more) break;
;         p = pn; it = itn;
;     }
.Lmy_cvr_rd:
	ds_read_b32 v82, v7 offset:0
	ds_read_b32 v83, v7 offset:132
	ds_read_b32 v86, v7 offset:264
	ds_read_b32 v91, v7 offset:396
	ds_read_b32 v96, v7 offset:528
	ds_read_b32 v97, v7 offset:660
	ds_read_b32 v78, v7 offset:792
	ds_read_b32 v2, v7 offset:924
	s_waitcnt lgkmcnt(0)
	v_cvt_pk_bf16_f32 v92, v82, v83
	v_cvt_pk_bf16_f32 v93, v86, v91
	v_cvt_pk_bf16_f32 v94, v96, v97
	v_cvt_pk_bf16_f32 v95, v78, v2
	global_store_dwordx4 v3, v[92:95], s[12:13]
	ds_read_b32 v82, v7 offset:64
	ds_read_b32 v83, v7 offset:196
	ds_read_b32 v86, v7 offset:328
	ds_read_b32 v91, v7 offset:460
	ds_read_b32 v96, v7 offset:592
	ds_read_b32 v97, v7 offset:724
	ds_read_b32 v78, v7 offset:856
	ds_read_b32 v2, v7 offset:988
	s_waitcnt lgkmcnt(0)
	v_cvt_pk_bf16_f32 v92, v82, v83
	v_cvt_pk_bf16_f32 v93, v86, v91
	v_cvt_pk_bf16_f32 v94, v96, v97
	v_cvt_pk_bf16_f32 v95, v78, v2
	global_store_dwordx4 v5, v[92:95], s[12:13]
	ds_read_b32 v82, v7 offset:4224
	ds_read_b32 v83, v7 offset:4356
	ds_read_b32 v86, v7 offset:4488
	ds_read_b32 v91, v7 offset:4620
	ds_read_b32 v96, v7 offset:4752
	ds_read_b32 v97, v7 offset:4884
	ds_read_b32 v78, v7 offset:5016
	ds_read_b32 v2, v7 offset:5148
	s_waitcnt lgkmcnt(0)
	v_cvt_pk_bf16_f32 v92, v82, v83
	v_cvt_pk_bf16_f32 v93, v86, v91
	v_cvt_pk_bf16_f32 v94, v96, v97
	v_cvt_pk_bf16_f32 v95, v78, v2
	global_store_dwordx4 v3, v[92:95], s[12:13] offset:64
	ds_read_b32 v82, v7 offset:4288
	ds_read_b32 v83, v7 offset:4420
	ds_read_b32 v86, v7 offset:4552
	ds_read_b32 v91, v7 offset:4684
	ds_read_b32 v96, v7 offset:4816
	ds_read_b32 v97, v7 offset:4948
	ds_read_b32 v78, v7 offset:5080
	ds_read_b32 v2, v7 offset:5212
	s_waitcnt lgkmcnt(0)
	v_cvt_pk_bf16_f32 v92, v82, v83
	v_cvt_pk_bf16_f32 v93, v86, v91
	v_cvt_pk_bf16_f32 v94, v96, v97
	v_cvt_pk_bf16_f32 v95, v78, v2
	global_store_dwordx4 v5, v[92:95], s[12:13] offset:64
	ds_read_b32 v82, v7 offset:8448
	ds_read_b32 v83, v7 offset:8580
	ds_read_b32 v86, v7 offset:8712
	ds_read_b32 v91, v7 offset:8844
	ds_read_b32 v96, v7 offset:8976
	ds_read_b32 v97, v7 offset:9108
	ds_read_b32 v78, v7 offset:9240
	ds_read_b32 v2, v7 offset:9372
	s_waitcnt lgkmcnt(0)
	v_cvt_pk_bf16_f32 v92, v82, v83
	v_cvt_pk_bf16_f32 v93, v86, v91
	v_cvt_pk_bf16_f32 v94, v96, v97
	v_cvt_pk_bf16_f32 v95, v78, v2
	global_store_dwordx4 v3, v[92:95], s[12:13] offset:128
	ds_read_b32 v82, v7 offset:8512
	ds_read_b32 v83, v7 offset:8644
	ds_read_b32 v86, v7 offset:8776
	ds_read_b32 v91, v7 offset:8908
	ds_read_b32 v96, v7 offset:9040
	ds_read_b32 v97, v7 offset:9172
	ds_read_b32 v78, v7 offset:9304
	ds_read_b32 v2, v7 offset:9436
	s_waitcnt lgkmcnt(0)
	v_cvt_pk_bf16_f32 v92, v82, v83
	v_cvt_pk_bf16_f32 v93, v86, v91
	v_cvt_pk_bf16_f32 v94, v96, v97
	v_cvt_pk_bf16_f32 v95, v78, v2
	global_store_dwordx4 v5, v[92:95], s[12:13] offset:128
	ds_read_b32 v82, v7 offset:12672
	ds_read_b32 v83, v7 offset:12804
	ds_read_b32 v86, v7 offset:12936
	ds_read_b32 v91, v7 offset:13068
	ds_read_b32 v96, v7 offset:13200
	ds_read_b32 v97, v7 offset:13332
	ds_read_b32 v78, v7 offset:13464
	ds_read_b32 v2, v7 offset:13596
	s_waitcnt lgkmcnt(0)
	v_cvt_pk_bf16_f32 v92, v82, v83
	v_cvt_pk_bf16_f32 v93, v86, v91
	v_cvt_pk_bf16_f32 v94, v96, v97
	v_cvt_pk_bf16_f32 v95, v78, v2
	global_store_dwordx4 v3, v[92:95], s[12:13] offset:192
	ds_read_b32 v82, v7 offset:12736
	ds_read_b32 v83, v7 offset:12868
	ds_read_b32 v86, v7 offset:13000
	ds_read_b32 v91, v7 offset:13132
	ds_read_b32 v96, v7 offset:13264
	ds_read_b32 v97, v7 offset:13396
	ds_read_b32 v78, v7 offset:13528
	ds_read_b32 v2, v7 offset:13660
	s_waitcnt lgkmcnt(0)
	v_cvt_pk_bf16_f32 v92, v82, v83
	v_cvt_pk_bf16_f32 v93, v86, v91
	v_cvt_pk_bf16_f32 v94, v96, v97
	v_cvt_pk_bf16_f32 v95, v78, v2
	global_store_dwordx4 v5, v[92:95], s[12:13] offset:192
	s_cmp_lt_u32 s3, 5632
	s_cbranch_scc1 .Lmy_cvr_loop
.Lmy_cvr_exit:
	s_waitcnt vmcnt(0) lgkmcnt(0)
.Lmy_cvr_done:
	s_mov_b64 s[4:5], s[0:1]
	s_load_dword s2, s[4:5], 0xd8
	s_waitcnt lgkmcnt(0)
	s_cmp_gt_i32 s2, s54
	s_cbranch_scc0 .LBB0_3386
	s_getpc_b64 s[98:99]
